# k40: k39 + attention unit loop uses one workgroup barrier per unit for the ticket hand-off instead of two
# speedup vs baseline: 1.0033x; 1.0008x over previous
; #define CTL WSP(unsigned, WS_CTL)
; __global__ void __launch_bounds__(NTHR, 2) hymba_fwd(Params P) {
;     ...
;         unsigned nxt_ui = 0u;
;         if (tid == 0) nxt_ui = atomicAdd(CTL + 64 + 64 * rep, 1u);
;         for (;;) {
;             asm volatile("s_waitcnt lgkmcnt(0)\n\ts_barrier" ::: "memory");
;             if (tid == 0) { uw[0] = nxt_ui; nxt_ui = atomicAdd(CTL + 64 + 64 * rep, 1u); }
;             asm volatile("s_waitcnt lgkmcnt(0)\n\ts_barrier" ::: "memory");
;             const int ui = __builtin_amdgcn_readfirstlane((int)uw[0]);
;             if (ui >= NUNITS) break;
.LBB0_721:
	s_waitcnt lgkmcnt(0)
	s_nop 0
	s_and_saveexec_b64 s[6:7], s[4:5]
	s_cbranch_execz .LBB0_725
	s_mov_b64 s[8:9], exec
	v_mov_b32_e32 v0, s21
	ds_write_b32 v0, v129
	v_mbcnt_lo_u32_b32 v0, s8, 0
	v_mbcnt_hi_u32_b32 v0, s9, v0
	v_cmp_eq_u32_e32 vcc, 0, v0
	s_and_saveexec_b64 s[10:11], vcc
	s_cbranch_execz .LBB0_724
	s_bcnt1_i32_b64 s8, s[8:9]
	v_mov_b32_e32 v2, s8
	global_atomic_add v129, v1, v2, s[92:93] offset:256 sc0
